# k1 + FoX attention loop: V fragment LDS reads hoisted to right after the QK MFMAs (free registers), softmax split by key half with early PV MFMAs
# baseline (speedup 1.0000x reference)
; template <int DK, int MODE, bool OUTF32> ...
;     ...
;             const unsigned char* kb = a_lds + cur * KBUF + (32 * kh + c) * KP + hi * 16;
;             constexpr bool HOISTK = true;
;             bf16x8 kf[NKS];
;             if (HOISTK) {
; #pragma unroll
;                 for (int s = 0; s < NKS; ++s) kf[s] = *(const bf16x8*)(kb + s * 32);
;             }
;             const unsigned char* vb = a_lds + OFF_V + cur * VBUF + c * VP + (32 * kh + 4 * hi) * 2;
;             bf16x8 vf[8];
;     ...
;             constexpr bool HOISTV = (DK == 128) && (MODE == 2 || MODE == 1);
;             if (HOISTV) A_VREADS(0, 3);
;             if (HOISTK) __builtin_amdgcn_sched_barrier(0);
; #pragma unroll
;             for (int s = 0; s < NKS; ++s) p = __builtin_amdgcn_mfma_f32_32x32x16_bf16(HOISTK ? kf[s] : *(const bf16x8*)(kb + s * 32), qf[s], p, 0, 0, 0);
;             if (HOISTV) { A_VREADS(3, 4); __builtin_amdgcn_sched_barrier(0); }
;             if (MODE == 0) {
;                 const float* ckp = (const float*)(a_lds + OFF_CK + cur * 256) + 32 * kh + 4 * hi;
; #pragma unroll
;                 for (int g = 0; g < 4; ++g) {
;                     const float4 ck = *(const float4*)(ckp + 8 * g);
;                     p[4 * g + 0] = fmaf(p[4 * g + 0], sc2, cq - ck.x); p[4 * g + 1] = fmaf(p[4 * g + 1], sc2, cq - ck.y);
;                     p[4 * g + 2] = fmaf(p[4 * g + 2], sc2, cq - ck.z); p[4 * g + 3] = fmaf(p[4 * g + 3], sc2, cq - ck.w);
;                 }
;                 if (64 * t + 32 * kh + 31 > qw0) {
;                     const int kbase = 64 * t + 32 * kh + 4 * hi;
; #pragma unroll
;                     for (int r = 0; r < 16; ++r) if (kbase + (r & 3) + 8 * (r >> 2) > qrow) p[r] = NEGINF;
;                 }
.LBB0_282:
	s_or_b64 exec, exec, s[12:13]
	v_add_u32_e32 v186, s14, v181
	s_and_b32 s16, s15, 1
	v_cmp_le_i32_e32 vcc, v186, v182
	s_and_saveexec_b64 s[46:47], vcc
	s_cbranch_execz .LBB0_288
	s_mul_i32 s17, s16, 0x4400
	v_add_u32_e32 v88, s17, v177
	ds_read_b128 v[84:87], v88
	ds_read_b128 v[188:191], v88 offset:32
	ds_read_b128 v[208:211], v88 offset:64
	ds_read_b128 v[212:215], v88 offset:96
	ds_read_b128 v[216:219], v88 offset:128
	ds_read_b128 v[220:223], v88 offset:160
	ds_read_b128 v[224:227], v88 offset:192
	ds_read_b128 v[228:231], v88 offset:224
	s_waitcnt lgkmcnt(7)
	v_mfma_f32_32x32x16_bf16 v[84:99], v[84:87], v[128:131], 0
	v_lshl_add_u32 v187, s16, 8, v173
	v_add_u32_e32 v186, 31, v186
	v_cmp_gt_i32_e32 vcc, v186, v159
	s_waitcnt lgkmcnt(6)
	v_mfma_f32_32x32x16_bf16 v[84:99], v[188:191], v[124:127], v[84:99]
	s_waitcnt lgkmcnt(5)
	v_mfma_f32_32x32x16_bf16 v[84:99], v[208:211], v[120:123], v[84:99]
	ds_read_b128 v[188:191], v187
	ds_read_b128 v[208:211], v187 offset:32
	s_waitcnt lgkmcnt(1)
	v_sub_f32_e32 v193, v1, v189
	v_sub_f32_e32 v192, v68, v188
	v_sub_f32_e32 v197, v77, v191
	v_mfma_f32_32x32x16_bf16 v[84:99], v[212:215], v[112:115], v[84:99]
	v_sub_f32_e32 v196, v78, v190
	s_waitcnt lgkmcnt(0)
	v_sub_f32_e32 v213, v75, v209
	v_sub_f32_e32 v212, v76, v208
	v_sub_f32_e32 v215, v73, v211
	v_sub_f32_e32 v214, v70, v210
	ds_read_b128 v[188:191], v187 offset:64
	ds_read_b128 v[208:211], v187 offset:96
	s_waitcnt lgkmcnt(1)
	v_sub_f32_e32 v189, v69, v189
	v_mfma_f32_32x32x16_bf16 v[84:99], v[216:219], v[116:119], v[84:99]
	v_sub_f32_e32 v188, v72, v188
	v_sub_f32_e32 v191, v71, v191
	v_sub_f32_e32 v190, v74, v190
	s_waitcnt lgkmcnt(0)
	v_sub_f32_e32 v209, v79, v209
	v_sub_f32_e32 v208, v80, v208
	v_sub_f32_e32 v211, v81, v211
	v_sub_f32_e32 v210, v82, v210
	v_mfma_f32_32x32x16_bf16 v[84:99], v[220:223], v[108:111], v[84:99]
	v_mfma_f32_32x32x16_bf16 v[84:99], v[224:227], v[104:107], v[84:99]
	v_mfma_f32_32x32x16_bf16 v[84:99], v[228:231], v[100:103], v[84:99]
	v_add_u32_e32 v246, s17, v170
	v_add_u32_e32 v247, 0xc800, v246
	v_add_u32_e32 v250, 0xd800, v246
	v_add_u32_e32 v251, 0xe800, v246
	v_add_u32_e32 v246, 0xf800, v246
	ds_read2_b64 v[234:237], v247 offset1:2
	ds_read2_b64 v[238:241], v247 offset0:4 offset1:6
	ds_read2_b64 v[242:245], v250 offset0:32 offset1:34
	ds_read2_b64 v[252:255], v250 offset0:36 offset1:38
	ds_read2_b64 v[224:227], v251 offset0:64 offset1:66
	ds_read2_b64 v[228:231], v251 offset0:68 offset1:70
	ds_read2_b64 v[216:219], v246 offset0:96 offset1:98
	ds_read2_b64 v[220:223], v246 offset0:100 offset1:102
	s_nop 1
	v_pk_fma_f32 v[98:99], v[98:99], s[24:25], v[210:211] op_sel_hi:[1,0,1]
	v_pk_fma_f32 v[96:97], v[96:97], s[24:25], v[208:209] op_sel_hi:[1,0,1]
	v_pk_fma_f32 v[94:95], v[94:95], s[24:25], v[190:191] op_sel_hi:[1,0,1]
	v_pk_fma_f32 v[92:93], v[92:93], s[24:25], v[188:189] op_sel_hi:[1,0,1]
	v_pk_fma_f32 v[90:91], v[90:91], s[24:25], v[214:215] op_sel_hi:[1,0,1]
	v_pk_fma_f32 v[88:89], v[88:89], s[24:25], v[212:213] op_sel_hi:[1,0,1]
	v_pk_fma_f32 v[86:87], v[86:87], s[24:25], v[196:197] op_sel_hi:[1,0,1]
	v_pk_fma_f32 v[84:85], v[84:85], s[24:25], v[192:193] op_sel_hi:[1,0,1]
	s_and_saveexec_b64 s[12:13], vcc
	s_cbranch_execz .LBB0_285
	v_add_u32_e32 v186, s14, v183
	v_cmp_lt_i32_e32 vcc, v186, v154
	v_add_u32_e32 v187, 2, v186
	s_nop 0
	v_cndmask_b32_e32 v85, v206, v85, vcc
	v_cmp_le_i32_e32 vcc, v186, v154
	s_nop 1
	v_cndmask_b32_e32 v84, v206, v84, vcc
	v_cmp_le_i32_e32 vcc, v187, v154
	v_add_u32_e32 v187, 3, v186
	s_nop 0
	v_cndmask_b32_e32 v86, v206, v86, vcc
	v_cmp_le_i32_e32 vcc, v187, v154
	v_add_u32_e32 v187, 8, v186
	s_nop 0
	v_cndmask_b32_e32 v87, v206, v87, vcc
	v_cmp_le_i32_e32 vcc, v187, v154
	v_add_u32_e32 v187, 9, v186
	s_nop 0
	v_cndmask_b32_e32 v88, v206, v88, vcc
	v_cmp_le_i32_e32 vcc, v187, v154
	v_add_u32_e32 v187, 10, v186
	s_nop 0
	v_cndmask_b32_e32 v89, v206, v89, vcc
	v_cmp_le_i32_e32 vcc, v187, v154
	v_add_u32_e32 v187, 11, v186
	s_nop 0
	v_cndmask_b32_e32 v90, v206, v90, vcc
	v_cmp_le_i32_e32 vcc, v187, v154
	v_add_u32_e32 v187, 16, v186
	s_nop 0
	v_cndmask_b32_e32 v91, v206, v91, vcc
	v_cmp_le_i32_e32 vcc, v187, v154
	v_add_u32_e32 v187, 17, v186
	s_nop 0
	v_cndmask_b32_e32 v92, v206, v92, vcc
	v_cmp_le_i32_e32 vcc, v187, v154
	v_add_u32_e32 v187, 18, v186
	s_nop 0
	v_cndmask_b32_e32 v93, v206, v93, vcc
	v_cmp_le_i32_e32 vcc, v187, v154
	v_add_u32_e32 v187, 19, v186
	s_nop 0
	v_cndmask_b32_e32 v94, v206, v94, vcc
	v_cmp_le_i32_e32 vcc, v187, v154
	v_add_u32_e32 v187, 24, v186
	s_nop 0
	v_cndmask_b32_e32 v95, v206, v95, vcc
	v_cmp_le_i32_e32 vcc, v187, v154
	v_add_u32_e32 v187, 25, v186
	s_nop 0
	v_cndmask_b32_e32 v96, v206, v96, vcc
	v_cmp_le_i32_e32 vcc, v187, v154
	v_add_u32_e32 v187, 26, v186
	v_add_u32_e32 v186, 27, v186
	v_cndmask_b32_e32 v97, v206, v97, vcc
	v_cmp_le_i32_e32 vcc, v187, v154
	s_nop 1
	v_cndmask_b32_e32 v98, v206, v98, vcc
	v_cmp_le_i32_e32 vcc, v186, v154
	s_nop 1
	v_cndmask_b32_e32 v99, v206, v99, vcc

; __device__ __forceinline__ unsigned cvtpk(float lo, float hi) { return __builtin_bit_cast(unsigned, __builtin_convertvector(f32x2_cv{lo, hi}, bf16x2_cv)); }
; __device__ __forceinline__ float dot2bf(unsigned w, unsigned x, float acc) { return __builtin_amdgcn_fdot2_f32_bf16(__builtin_bit_cast(bf16x2_t, w), __builtin_bit_cast(bf16x2_t, x), acc, false); }
; template <int DK, int MODE, bool OUTF32> ...
;     ...
;             for (int r = 0; r < 16; ++r) p[r] = __builtin_amdgcn_exp2f((MODE == 2) ? fmaf(p[r], sc2, -m) : (p[r] - m));
;             bf16x8 pb0, pb1;
;             { const unsigned w0 = cvtpk(p[0], p[1]), w1 = cvtpk(p[2], p[3]), w2 = cvtpk(p[4], p[5]), w3 = cvtpk(p[6], p[7]);
;               const uint4 u = make_uint4(w0, w1, w2, w3); pb0 = *reinterpret_cast<const bf16x8*>(&u); }
;             { const unsigned w0 = cvtpk(p[8], p[9]), w1 = cvtpk(p[10], p[11]), w2 = cvtpk(p[12], p[13]), w3 = cvtpk(p[14], p[15]);
;               const uint4 u = make_uint4(w0, w1, w2, w3); pb1 = *reinterpret_cast<const bf16x8*>(&u); }
;             {
;                 const uint4 ua = *reinterpret_cast<const uint4*>(&pb0), ub = *reinterpret_cast<const uint4*>(&pb1);
;                 float ps = 0.f, ps2 = 0.f;
;                 ps = dot2bf(ua.x, 0x3f803f80u, ps); ps2 = dot2bf(ua.y, 0x3f803f80u, ps2); ps = dot2bf(ua.z, 0x3f803f80u, ps); ps2 = dot2bf(ua.w, 0x3f803f80u, ps2);
;                 ps = dot2bf(ub.x, 0x3f803f80u, ps); ps2 = dot2bf(ub.y, 0x3f803f80u, ps2); ps = dot2bf(ub.z, 0x3f803f80u, ps); ps2 = dot2bf(ub.w, 0x3f803f80u, ps2);
;                 l += ps + ps2;
;             }
;             if (HOISTK && !HOISTV) A_VREADS(0, 4);
;             if (HOISTK) __builtin_amdgcn_sched_barrier(0);
; #pragma unroll
;             for (int db = 0; db < 4; ++db) {
;                 if (!HOISTK) { A_VREADS(db, db + 1); }
;                 o[db] = __builtin_amdgcn_mfma_f32_32x32x16_bf16(vf[2 * db], pb0, o[db], 0, 0, 0);
;                 o[db] = __builtin_amdgcn_mfma_f32_32x32x16_bf16(vf[2 * db + 1], pb1, o[db], 0, 0, 0);
;             }
.LBB0_287:
	v_sub_f32_e32 v84, v84, v171
	v_sub_f32_e32 v85, v85, v171
	v_sub_f32_e32 v86, v86, v171
	v_sub_f32_e32 v87, v87, v171
	v_sub_f32_e32 v88, v88, v171
	v_sub_f32_e32 v89, v89, v171
	v_sub_f32_e32 v90, v90, v171
	v_sub_f32_e32 v91, v91, v171
	v_exp_f32_e32 v84, v84
	v_exp_f32_e32 v85, v85
	v_exp_f32_e32 v86, v86
	v_exp_f32_e32 v87, v87
	v_exp_f32_e32 v88, v88
	v_exp_f32_e32 v89, v89
	v_exp_f32_e32 v90, v90
	v_exp_f32_e32 v91, v91
	v_cvt_pk_bf16_f32 v84, v84, v85
	v_cvt_pk_bf16_f32 v85, v86, v87
	v_cvt_pk_bf16_f32 v86, v88, v89
	v_cvt_pk_bf16_f32 v87, v90, v91
	v_mov_b32_e32 v196, 0
	v_mov_b32_e32 v197, 0
	v_dot2c_f32_bf16_e32 v196, 0x3f803f80, v84
	v_dot2c_f32_bf16_e32 v197, 0x3f803f80, v85
	v_dot2c_f32_bf16_e32 v196, 0x3f803f80, v86
	v_dot2c_f32_bf16_e32 v197, 0x3f803f80, v87
	s_waitcnt lgkmcnt(7)
	v_mfma_f32_32x32x16_bf16 v[52:67], v[234:237], v[84:87], v[52:67]
	s_waitcnt lgkmcnt(5)
	v_mfma_f32_32x32x16_bf16 v[20:35], v[242:245], v[84:87], v[20:35]
	s_waitcnt lgkmcnt(3)
	v_mfma_f32_32x32x16_bf16 v[36:51], v[224:227], v[84:87], v[36:51]
	s_waitcnt lgkmcnt(1)
	v_mfma_f32_32x32x16_bf16 v[4:19], v[216:219], v[84:87], v[4:19]
	v_sub_f32_e32 v92, v92, v171
	v_sub_f32_e32 v93, v93, v171
	v_sub_f32_e32 v94, v94, v171
	v_sub_f32_e32 v95, v95, v171
	v_sub_f32_e32 v96, v96, v171
	v_sub_f32_e32 v97, v97, v171
	v_sub_f32_e32 v98, v98, v171
	v_sub_f32_e32 v99, v99, v171
	v_exp_f32_e32 v92, v92
	v_exp_f32_e32 v93, v93
	v_exp_f32_e32 v94, v94
	v_exp_f32_e32 v95, v95
	v_exp_f32_e32 v96, v96
	v_exp_f32_e32 v97, v97
	v_exp_f32_e32 v98, v98
	v_exp_f32_e32 v99, v99
	v_cvt_pk_bf16_f32 v88, v92, v93
	v_cvt_pk_bf16_f32 v89, v94, v95
	v_cvt_pk_bf16_f32 v90, v96, v97
	v_cvt_pk_bf16_f32 v91, v98, v99
	v_dot2c_f32_bf16_e32 v196, 0x3f803f80, v88
	v_dot2c_f32_bf16_e32 v197, 0x3f803f80, v89
	v_dot2c_f32_bf16_e32 v196, 0x3f803f80, v90
	v_dot2c_f32_bf16_e32 v197, 0x3f803f80, v91
	s_nop 2
	v_add_f32_e32 v195, v196, v197
	v_mfma_f32_32x32x16_bf16 v[52:67], v[238:241], v[88:91], v[52:67]
	v_add_f32_e32 v169, v169, v195
	v_mfma_f32_32x32x16_bf16 v[20:35], v[252:255], v[88:91], v[20:35]
	v_mfma_f32_32x32x16_bf16 v[36:51], v[228:231], v[88:91], v[36:51]
	s_waitcnt lgkmcnt(0)
	v_mfma_f32_32x32x16_bf16 v[4:19], v[220:223], v[88:91], v[4:19]
